# 32x32x16 attention loop: bf16 pack conversions woven into the MFMA gaps
# baseline (speedup 1.0000x reference)
.Lattn_nf_loop:
	s_and_b32 s10, s15, 1
	s_mul_i32 s6, s10, 0x8800
	v_add_u32_e32 v136, s6, v137
	v_add_u32_e32 v170, s6, v183
	s_sub_u32 s10, 0x8800, s6
	ds_read_b128 v[98:101], v136 offset:0
	ds_read_b128 v[102:105], v136 offset:32
	ds_read_b128 v[106:109], v136 offset:64
	ds_read_b128 v[110:113], v136 offset:96
	v_add_u32_e32 v171, s10, v126
	v_add_u32_e32 v173, s10, v127
	global_load_dwordx4 v[82:85], v124, s[64:65]
	global_load_dwordx4 v[86:89], v124, s[66:67]
	global_load_dwordx4 v[90:93], v124, s[68:69]
	global_load_dwordx4 v[94:97], v124, s[70:71]
	v_add_u32_e32 v124, s36, v124
	s_waitcnt lgkmcnt(3)
	v_mfma_f32_32x32x16_bf16 v[138:153], v[98:101], v[10:13], 0
	ds_read_b128 v[98:101], v136 offset:8704
	s_waitcnt lgkmcnt(3)
	v_mfma_f32_32x32x16_bf16 v[138:153], v[102:105], v[14:17], v[138:153]
	ds_read_b128 v[102:105], v136 offset:8736
	s_waitcnt lgkmcnt(3)
	v_mfma_f32_32x32x16_bf16 v[138:153], v[106:109], v[2:5], v[138:153]
	ds_read_b128 v[106:109], v136 offset:8768
	s_waitcnt lgkmcnt(3)
	v_mfma_f32_32x32x16_bf16 v[138:153], v[110:113], v[6:9], v[138:153]
	ds_read_b128 v[110:113], v136 offset:8800
	ds_read_b128 v[128:131], v170 offset:0
	ds_read_b128 v[184:187], v170 offset:8704
	ds_read_b128 v[188:191], v170 offset:17408
	ds_read_b128 v[192:195], v170 offset:26112
	s_waitcnt lgkmcnt(7)
	v_mfma_f32_32x32x16_bf16 v[154:169], v[98:101], v[10:13], 0
	ds_read_b128 v[98:101], v136 offset:17408
	s_nop 3
	v_exp_f32_e32 v138, v138
	v_exp_f32_e32 v139, v139
	v_exp_f32_e32 v140, v140
	v_exp_f32_e32 v141, v141
	v_exp_f32_e32 v142, v142
	v_exp_f32_e32 v143, v143
	v_exp_f32_e32 v144, v144
	v_exp_f32_e32 v145, v145
	v_add_f32_e32 v122, v138, v122
	v_add_f32_e32 v122, v139, v122
	s_waitcnt lgkmcnt(7)
	v_mfma_f32_32x32x16_bf16 v[154:169], v[102:105], v[14:17], v[154:169]
	ds_read_b128 v[102:105], v136 offset:17440
	v_add_f32_e32 v122, v140, v122
	v_add_f32_e32 v122, v141, v122
	v_add_f32_e32 v122, v142, v122
	v_add_f32_e32 v122, v143, v122
	v_add_f32_e32 v122, v144, v122
	v_add_f32_e32 v122, v145, v122
	v_cvt_pk_bf16_f32 v114, v138, v139
	v_cvt_pk_bf16_f32 v115, v140, v141
	v_cvt_pk_bf16_f32 v116, v142, v143
	v_cvt_pk_bf16_f32 v117, v144, v145
	ds_read_b128 v[196:199], v170 offset:32
	ds_read_b128 v[216:219], v170 offset:8736
	ds_read_b128 v[200:203], v170 offset:17440
	ds_read_b128 v[204:207], v170 offset:26144
	s_waitcnt lgkmcnt(11)
	v_mfma_f32_32x32x16_bf16 v[154:169], v[106:109], v[2:5], v[154:169]
	ds_read_b128 v[106:109], v136 offset:17472
	v_exp_f32_e32 v146, v146
	v_exp_f32_e32 v147, v147
	v_exp_f32_e32 v148, v148
	v_exp_f32_e32 v149, v149
	s_waitcnt lgkmcnt(11)
	v_mfma_f32_32x32x16_bf16 v[154:169], v[110:113], v[6:9], v[154:169]
	ds_read_b128 v[110:113], v136 offset:17504
	v_exp_f32_e32 v150, v150
	v_exp_f32_e32 v151, v151
	v_exp_f32_e32 v152, v152
	v_exp_f32_e32 v153, v153
	s_waitcnt lgkmcnt(11)
	v_mfma_f32_32x32x16_bf16 v[18:33], v[128:131], v[114:117], v[18:33]
	v_add_f32_e32 v122, v146, v122
	v_add_f32_e32 v122, v147, v122
	v_add_f32_e32 v122, v148, v122
	s_waitcnt lgkmcnt(10)
	v_mfma_f32_32x32x16_bf16 v[34:49], v[184:187], v[114:117], v[34:49]
	v_add_f32_e32 v122, v149, v122
	v_add_f32_e32 v122, v150, v122
	v_add_f32_e32 v122, v151, v122
	s_waitcnt lgkmcnt(9)
	v_mfma_f32_32x32x16_bf16 v[50:65], v[188:191], v[114:117], v[50:65]
	v_add_f32_e32 v122, v152, v122
	v_add_f32_e32 v122, v153, v122
	v_cvt_pk_bf16_f32 v118, v146, v147
	s_waitcnt lgkmcnt(8)
	v_mfma_f32_32x32x16_bf16 v[66:81], v[192:195], v[114:117], v[66:81]
	v_cvt_pk_bf16_f32 v119, v148, v149
	v_cvt_pk_bf16_f32 v120, v150, v151
	v_cvt_pk_bf16_f32 v121, v152, v153
	ds_read_b128 v[128:131], v170 offset:64
	ds_read_b128 v[184:187], v170 offset:8768
	ds_read_b128 v[188:191], v170 offset:17472
	ds_read_b128 v[192:195], v170 offset:26176
	s_waitcnt lgkmcnt(11)
	v_mfma_f32_32x32x16_bf16 v[138:153], v[98:101], v[10:13], 0
	ds_read_b128 v[98:101], v136 offset:26112
	v_exp_f32_e32 v154, v154
	v_exp_f32_e32 v155, v155
	v_exp_f32_e32 v156, v156
	v_exp_f32_e32 v157, v157
	s_waitcnt lgkmcnt(11)
	v_mfma_f32_32x32x16_bf16 v[138:153], v[102:105], v[14:17], v[138:153]
	ds_read_b128 v[102:105], v136 offset:26144
	v_exp_f32_e32 v158, v158
	v_exp_f32_e32 v159, v159
	v_exp_f32_e32 v160, v160
	v_exp_f32_e32 v161, v161
	s_waitcnt lgkmcnt(11)
	v_mfma_f32_32x32x16_bf16 v[18:33], v[196:199], v[118:121], v[18:33]
	v_add_f32_e32 v122, v154, v122
	v_add_f32_e32 v122, v155, v122
	v_add_f32_e32 v122, v156, v122
	s_waitcnt lgkmcnt(10)
	v_mfma_f32_32x32x16_bf16 v[34:49], v[216:219], v[118:121], v[34:49]
	v_add_f32_e32 v122, v157, v122
	v_add_f32_e32 v122, v158, v122
	v_add_f32_e32 v122, v159, v122
	s_waitcnt lgkmcnt(9)
	v_mfma_f32_32x32x16_bf16 v[50:65], v[200:203], v[118:121], v[50:65]
	v_add_f32_e32 v122, v160, v122
	v_add_f32_e32 v122, v161, v122
	v_cvt_pk_bf16_f32 v114, v154, v155
	s_waitcnt lgkmcnt(8)
	v_mfma_f32_32x32x16_bf16 v[66:81], v[204:207], v[118:121], v[66:81]
	v_cvt_pk_bf16_f32 v115, v156, v157
	v_cvt_pk_bf16_f32 v116, v158, v159
	v_cvt_pk_bf16_f32 v117, v160, v161
	ds_read_b128 v[196:199], v170 offset:96
	ds_read_b128 v[216:219], v170 offset:8800
	ds_read_b128 v[200:203], v170 offset:17504
	ds_read_b128 v[204:207], v170 offset:26208
	s_waitcnt lgkmcnt(11)
	v_mfma_f32_32x32x16_bf16 v[138:153], v[106:109], v[2:5], v[138:153]
	ds_read_b128 v[106:109], v136 offset:26176
	v_exp_f32_e32 v162, v162
	v_exp_f32_e32 v163, v163
	v_exp_f32_e32 v164, v164
	v_exp_f32_e32 v165, v165
	s_waitcnt lgkmcnt(11)
	v_mfma_f32_32x32x16_bf16 v[138:153], v[110:113], v[6:9], v[138:153]
	ds_read_b128 v[110:113], v136 offset:26208
	v_exp_f32_e32 v166, v166
	v_exp_f32_e32 v167, v167
	v_exp_f32_e32 v168, v168
	v_exp_f32_e32 v169, v169
	s_waitcnt lgkmcnt(11)
	v_mfma_f32_32x32x16_bf16 v[18:33], v[128:131], v[114:117], v[18:33]
	v_add_f32_e32 v122, v162, v122
	v_add_f32_e32 v122, v163, v122
	v_add_f32_e32 v122, v164, v122
	s_waitcnt lgkmcnt(10)
	v_mfma_f32_32x32x16_bf16 v[34:49], v[184:187], v[114:117], v[34:49]
	v_add_f32_e32 v122, v165, v122
	v_add_f32_e32 v122, v166, v122
	v_add_f32_e32 v122, v167, v122
	s_waitcnt lgkmcnt(9)
	v_mfma_f32_32x32x16_bf16 v[50:65], v[188:191], v[114:117], v[50:65]
	v_add_f32_e32 v122, v168, v122
	v_add_f32_e32 v122, v169, v122
	v_cvt_pk_bf16_f32 v118, v162, v163
	s_waitcnt lgkmcnt(8)
	v_mfma_f32_32x32x16_bf16 v[66:81], v[192:195], v[114:117], v[66:81]
	v_cvt_pk_bf16_f32 v119, v164, v165
	v_cvt_pk_bf16_f32 v120, v166, v167
	v_cvt_pk_bf16_f32 v121, v168, v169
	ds_read_b128 v[128:131], v170 offset:128
	ds_read_b128 v[184:187], v170 offset:8832
	ds_read_b128 v[188:191], v170 offset:17536
	ds_read_b128 v[192:195], v170 offset:26240
	s_waitcnt lgkmcnt(11)
	v_mfma_f32_32x32x16_bf16 v[154:169], v[98:101], v[10:13], 0
	v_exp_f32_e32 v138, v138
	v_exp_f32_e32 v139, v139
	v_exp_f32_e32 v140, v140
	s_waitcnt lgkmcnt(10)
	v_mfma_f32_32x32x16_bf16 v[154:169], v[102:105], v[14:17], v[154:169]
	v_exp_f32_e32 v141, v141
	v_exp_f32_e32 v142, v142
	v_exp_f32_e32 v143, v143
	s_waitcnt lgkmcnt(9)
	v_mfma_f32_32x32x16_bf16 v[18:33], v[196:199], v[118:121], v[18:33]
	v_exp_f32_e32 v144, v144
	v_exp_f32_e32 v145, v145
	v_add_f32_e32 v122, v138, v122
	s_waitcnt vmcnt(3)
	ds_write_b128 v171, v[82:85] offset:0
	s_waitcnt vmcnt(2)
	ds_write_b128 v171, v[86:89] offset:8704
	s_waitcnt vmcnt(1)
	ds_write_b128 v171, v[90:93] offset:17408
	s_waitcnt vmcnt(0)
	ds_write_b128 v171, v[94:97] offset:26112
	v_add_f32_e32 v122, v139, v122
	v_add_f32_e32 v122, v140, v122
	v_add_f32_e32 v122, v141, v122
	s_waitcnt lgkmcnt(12)
	v_mfma_f32_32x32x16_bf16 v[34:49], v[216:219], v[118:121], v[34:49]
	v_add_f32_e32 v122, v142, v122
	v_add_f32_e32 v122, v143, v122
	v_add_f32_e32 v122, v144, v122
	s_waitcnt lgkmcnt(11)
	v_mfma_f32_32x32x16_bf16 v[50:65], v[200:203], v[118:121], v[50:65]
	v_add_f32_e32 v122, v145, v122
	v_cvt_pk_bf16_f32 v114, v138, v139
	v_cvt_pk_bf16_f32 v115, v140, v141
	s_waitcnt lgkmcnt(10)
	v_mfma_f32_32x32x16_bf16 v[66:81], v[204:207], v[118:121], v[66:81]
	v_cvt_pk_bf16_f32 v116, v142, v143
	v_cvt_pk_bf16_f32 v117, v144, v145
	ds_read_b128 v[196:199], v170 offset:160
	ds_read_b128 v[216:219], v170 offset:8864
	ds_read_b128 v[200:203], v170 offset:17568
	ds_read_b128 v[204:207], v170 offset:26272
	s_waitcnt lgkmcnt(13)
	v_mfma_f32_32x32x16_bf16 v[154:169], v[106:109], v[2:5], v[154:169]
	v_exp_f32_e32 v146, v146
	v_exp_f32_e32 v147, v147
	v_exp_f32_e32 v148, v148
	s_waitcnt lgkmcnt(12)
	v_mfma_f32_32x32x16_bf16 v[154:169], v[110:113], v[6:9], v[154:169]
	v_exp_f32_e32 v149, v149
	v_exp_f32_e32 v150, v150
	v_exp_f32_e32 v151, v151
	s_waitcnt lgkmcnt(11)
	v_mfma_f32_32x32x16_bf16 v[18:33], v[128:131], v[114:117], v[18:33]
	v_exp_f32_e32 v152, v152
	v_exp_f32_e32 v153, v153
	v_add_f32_e32 v122, v146, v122
	global_load_dwordx4 v[82:85], v125, s[72:73]
	global_load_dwordx4 v[86:89], v125, s[74:75]
	global_load_dwordx4 v[90:93], v125, s[76:77]
	global_load_dwordx4 v[94:97], v125, s[78:79]
	v_add_u32_e32 v125, s38, v125
	v_add_f32_e32 v122, v147, v122
	v_add_f32_e32 v122, v148, v122
	v_add_f32_e32 v122, v149, v122
	s_waitcnt lgkmcnt(10)
	v_mfma_f32_32x32x16_bf16 v[34:49], v[184:187], v[114:117], v[34:49]
	v_add_f32_e32 v122, v150, v122
	v_add_f32_e32 v122, v151, v122
	v_add_f32_e32 v122, v152, v122
	s_waitcnt lgkmcnt(9)
	v_mfma_f32_32x32x16_bf16 v[50:65], v[188:191], v[114:117], v[50:65]
	v_add_f32_e32 v122, v153, v122
	v_cvt_pk_bf16_f32 v118, v146, v147
	v_cvt_pk_bf16_f32 v119, v148, v149
	s_waitcnt lgkmcnt(8)
	v_mfma_f32_32x32x16_bf16 v[66:81], v[192:195], v[114:117], v[66:81]
	v_cvt_pk_bf16_f32 v120, v150, v151
	v_cvt_pk_bf16_f32 v121, v152, v153
	ds_read_b128 v[128:131], v170 offset:192
	ds_read_b128 v[184:187], v170 offset:8896
	ds_read_b128 v[188:191], v170 offset:17600
	ds_read_b128 v[192:195], v170 offset:26304
	s_waitcnt lgkmcnt(7)
	v_mfma_f32_32x32x16_bf16 v[18:33], v[196:199], v[118:121], v[18:33]
	v_exp_f32_e32 v154, v154
	v_exp_f32_e32 v155, v155
	v_exp_f32_e32 v156, v156
	v_exp_f32_e32 v157, v157
	v_exp_f32_e32 v158, v158
	s_waitcnt lgkmcnt(6)
	v_mfma_f32_32x32x16_bf16 v[34:49], v[216:219], v[118:121], v[34:49]
	v_exp_f32_e32 v159, v159
	v_exp_f32_e32 v160, v160
	v_exp_f32_e32 v161, v161
	v_add_f32_e32 v122, v154, v122
	v_add_f32_e32 v122, v155, v122
	s_waitcnt lgkmcnt(5)
	v_mfma_f32_32x32x16_bf16 v[50:65], v[200:203], v[118:121], v[50:65]
	v_add_f32_e32 v122, v156, v122
	v_add_f32_e32 v122, v157, v122
	v_add_f32_e32 v122, v158, v122
	v_add_f32_e32 v122, v159, v122
	v_add_f32_e32 v122, v160, v122
	s_waitcnt lgkmcnt(4)
	v_mfma_f32_32x32x16_bf16 v[66:81], v[204:207], v[118:121], v[66:81]
	v_add_f32_e32 v122, v161, v122
	v_cvt_pk_bf16_f32 v114, v154, v155
	v_cvt_pk_bf16_f32 v115, v156, v157
	v_cvt_pk_bf16_f32 v116, v158, v159
	v_cvt_pk_bf16_f32 v117, v160, v161
	ds_read_b128 v[196:199], v170 offset:224
	ds_read_b128 v[216:219], v170 offset:8928
	ds_read_b128 v[200:203], v170 offset:17632
	ds_read_b128 v[204:207], v170 offset:26336
	s_waitcnt lgkmcnt(7)
	v_mfma_f32_32x32x16_bf16 v[18:33], v[128:131], v[114:117], v[18:33]
	v_exp_f32_e32 v162, v162
	v_exp_f32_e32 v163, v163
	v_exp_f32_e32 v164, v164
	v_exp_f32_e32 v165, v165
	v_exp_f32_e32 v166, v166
	s_waitcnt lgkmcnt(6)
	v_mfma_f32_32x32x16_bf16 v[34:49], v[184:187], v[114:117], v[34:49]
	v_exp_f32_e32 v167, v167
	v_exp_f32_e32 v168, v168
	v_exp_f32_e32 v169, v169
	v_add_f32_e32 v122, v162, v122
	v_add_f32_e32 v122, v163, v122
	s_waitcnt lgkmcnt(5)
	v_mfma_f32_32x32x16_bf16 v[50:65], v[188:191], v[114:117], v[50:65]
	v_add_f32_e32 v122, v164, v122
	v_add_f32_e32 v122, v165, v122
	v_add_f32_e32 v122, v166, v122
	v_add_f32_e32 v122, v167, v122
	v_add_f32_e32 v122, v168, v122
	s_waitcnt lgkmcnt(4)
	v_mfma_f32_32x32x16_bf16 v[66:81], v[192:195], v[114:117], v[66:81]
	v_add_f32_e32 v122, v169, v122
	v_cvt_pk_bf16_f32 v118, v162, v163
	v_cvt_pk_bf16_f32 v119, v164, v165
	v_cvt_pk_bf16_f32 v120, v166, v167
	v_cvt_pk_bf16_f32 v121, v168, v169
	s_waitcnt lgkmcnt(3)
	s_nop 0
	v_mfma_f32_32x32x16_bf16 v[18:33], v[196:199], v[118:121], v[18:33]
	s_waitcnt lgkmcnt(2)
	v_mfma_f32_32x32x16_bf16 v[34:49], v[216:219], v[118:121], v[34:49]
	s_waitcnt vmcnt(3)
	ds_write_b128 v173, v[82:85] offset:0
	s_waitcnt vmcnt(2)
	ds_write_b128 v173, v[86:89] offset:8704
	s_waitcnt vmcnt(1)
	ds_write_b128 v173, v[90:93] offset:17408
	s_waitcnt vmcnt(0)
	ds_write_b128 v173, v[94:97] offset:26112
	s_waitcnt lgkmcnt(5)
	v_mfma_f32_32x32x16_bf16 v[50:65], v[200:203], v[118:121], v[50:65]
	s_waitcnt lgkmcnt(4)
	v_mfma_f32_32x32x16_bf16 v[66:81], v[204:207], v[118:121], v[66:81]
	s_waitcnt lgkmcnt(0)
	s_barrier
	s_add_i32 s15, s15, 1
	s_cmp_eq_u32 s15, 34
	s_cbranch_scc0 .Lattn_nf_loop
	v_readlane_b32 s64, v175, 0
	v_readlane_b32 s65, v175, 1
	v_readlane_b32 s66, v175, 2
	v_readlane_b32 s67, v175, 3
	v_readlane_b32 s68, v175, 4
	v_readlane_b32 s69, v175, 5
	v_readlane_b32 s70, v175, 6
	v_readlane_b32 s71, v175, 7
	v_readlane_b32 s72, v175, 8
	v_readlane_b32 s73, v175, 9
	v_readlane_b32 s74, v175, 10
	v_readlane_b32 s75, v175, 11
	v_readlane_b32 s76, v175, 12
	v_readlane_b32 s77, v175, 13
	v_readlane_b32 s78, v175, 14
	v_readlane_b32 s79, v175, 15
	s_nop 4
	v_add_f32_e32 v186, v132, v134
	v_add_f32_e32 v184, v133, v135
	ds_bpermute_b32 v187, v172, v186
	ds_bpermute_b32 v185, v172, v184
	s_mov_b32 s10, 0x3fb8aa3b
	s_mov_b32 s11, 0xc2ce8ed0
	s_mov_b32 s6, 0x42b17218
	v_cmp_eq_u32_e64 s[40:41], 0, v179
	s_lshl_b32 s30, s14, 1
	v_lshlrev_b32_e32 v196, 3, v178
	v_mov_b32_e32 v197, 0
	v_lshlrev_b32_e32 v198, 4, v179
	v_or3_b32 v198, v198, v177, v180
	v_ashrrev_i32_e32 v199, 31, v198
	v_lshlrev_b64 v[198:199], 11, v[198:199]
	s_mov_b64 s[100:101], 0x18a10000
	v_lshl_add_u64 v[198:199], s[42:43], 0, v[198:199]
	v_lshl_add_u64 v[198:199], v[198:199], 0, s[30:31]
	v_lshl_add_u64 v[198:199], v[198:199], 0, v[196:197]
	v_lshl_add_u64 v[198:199], v[198:199], 0, s[100:101]
	global_load_dwordx2 v[146:147], v[198:199], off
	global_load_dwordx2 v[148:149], v[198:199], off offset:32
	global_load_dwordx2 v[150:151], v[198:199], off offset:64
	global_load_dwordx2 v[152:153], v[198:199], off offset:96
	global_load_dwordx2 v[188:189], v[198:199], off offset:128
	global_load_dwordx2 v[190:191], v[198:199], off offset:160
	global_load_dwordx2 v[192:193], v[198:199], off offset:192
	global_load_dwordx2 v[194:195], v[198:199], off offset:224
	s_mov_b64 s[100:101], exec
	s_and_b64 exec, exec, s[4:5]
	s_cbranch_execz .Lpop_skip
	v_readlane_b32 s14, v255, 22
	v_readlane_b32 s15, v255, 23
	v_mov_b32_e32 v224, 1
	s_nop 4
	global_atomic_add v224, v0, v224, s[14:15] sc0
